# baseline (speedup 1.0000x reference)
; __device__ __forceinline__ int accrow(int reg, int lh) { return (reg & 3) + 8 * (reg >> 2) + 4 * lh; }
; __device__ void ssd_out_item(const Params& p, int item, char* smem) {
;     ...
;     {
;       const int pp = tid >> 2, qu = tid & 3;
;       const uint4* src = (const uint4*)(p.xcT + ((size_t)(b * 128 + c) * 1024 + h * 64 + pp) * 128 + qu * 32);
; #pragma unroll
;       for (int i = 0; i < 4; ++i) *(uint4*)(xT + pp * 136 + qu * 32 + i * 8) = src[i];
;     }
;     __syncthreads();
;     f32x16 yd[2] = {zero16(), zero16()};
;     const u16* pv = p.prev + ((size_t)((b * 128 + c) * 16 + h)) * 8192;
; #pragma unroll
;     for (int ks = 0; ks < 8; ++ks) {
; #pragma unroll
;       for (int j = 0; j < 2; ++j) {
;         s16x8 bb = *(const s16x8*)(pv + (j * 32 + lr) * 128 + ks * 16 + lh * 8);
;         yd[j] = mfma32(cf[ks], bb, yd[j]);
;       }
;     }
; #pragma unroll
;     for (int r = 0; r < 16; ++r) {
;       const float e = __expf(ac[wv * 32 + accrow(r, lh)]);
;       yd[0][r] *= e; yd[1][r] *= e;
;     }
.LBB0_593:
	s_or_b64 exec, exec, vcc
	v_lshl_add_u64 v[68:69], v[142:143], 0, s[80:81]
	ds_write_b16 v186, v64 offset:35008
	s_waitcnt lgkmcnt(14)
	global_load_dwordx4 v[64:67], v[68:69], off
	global_load_dwordx4 v[226:229], v[68:69], off offset:16
	global_load_dwordx4 v[230:233], v[68:69], off offset:32
	global_load_dwordx4 v[234:237], v[68:69], off offset:48
	v_lshl_add_u64 v[216:217], v[136:137], 0, s[80:81]
	s_movk_i32 s77, 0x2000
	v_add_co_u32_e32 v218, vcc, s77, v216
	s_nop 1
	v_addc_co_u32_e32 v219, vcc, 0, v217, vcc
	s_waitcnt vmcnt(3)
	ds_write_b128 v169, v[64:67]
	s_waitcnt vmcnt(2)
	ds_write_b128 v187, v[226:229]
	s_waitcnt vmcnt(1)
	ds_write_b128 v188, v[230:233]
	s_waitcnt vmcnt(0)
	ds_write_b128 v189, v[234:237]
	s_waitcnt lgkmcnt(0)
	s_barrier
	global_load_dwordx4 v[144:147], v[216:217], off
	global_load_dwordx4 v[226:229], v[218:219], off
	global_load_dwordx4 v[230:233], v[216:217], off offset:32
	global_load_dwordx4 v[234:237], v[218:219], off offset:32
	global_load_dwordx4 v[238:241], v[216:217], off offset:64
	global_load_dwordx4 v[242:245], v[218:219], off offset:64
	global_load_dwordx4 v[246:249], v[216:217], off offset:96
	s_waitcnt vmcnt(6)
	v_mfma_f32_32x32x16_bf16 v[80:95], v[96:99], v[144:147], 0
	global_load_dwordx4 v[144:147], v[218:219], off offset:96
	s_waitcnt vmcnt(6)
	v_mfma_f32_32x32x16_bf16 v[64:79], v[96:99], v[226:229], 0
	global_load_dwordx4 v[226:229], v[216:217], off offset:128
	s_waitcnt vmcnt(6)
	v_mfma_f32_32x32x16_bf16 v[80:95], v[100:103], v[230:233], v[80:95]
	global_load_dwordx4 v[230:233], v[218:219], off offset:128
	s_waitcnt vmcnt(6)
	v_mfma_f32_32x32x16_bf16 v[64:79], v[100:103], v[234:237], v[64:79]
	global_load_dwordx4 v[234:237], v[216:217], off offset:160
	s_waitcnt vmcnt(6)
	v_mfma_f32_32x32x16_bf16 v[80:95], v[104:107], v[238:241], v[80:95]
	global_load_dwordx4 v[238:241], v[218:219], off offset:160
	s_waitcnt vmcnt(6)
	v_mfma_f32_32x32x16_bf16 v[64:79], v[104:107], v[242:245], v[64:79]
	global_load_dwordx4 v[242:245], v[216:217], off offset:192
	s_waitcnt vmcnt(6)
	v_mfma_f32_32x32x16_bf16 v[80:95], v[108:111], v[246:249], v[80:95]
	global_load_dwordx4 v[246:249], v[218:219], off offset:192
	s_waitcnt vmcnt(6)
	v_mfma_f32_32x32x16_bf16 v[64:79], v[108:111], v[144:147], v[64:79]
	global_load_dwordx4 v[144:147], v[216:217], off offset:224
	s_waitcnt vmcnt(6)
	v_mfma_f32_32x32x16_bf16 v[80:95], v[112:115], v[226:229], v[80:95]
	global_load_dwordx4 v[226:229], v[218:219], off offset:224
	s_waitcnt vmcnt(6)
	v_mfma_f32_32x32x16_bf16 v[64:79], v[112:115], v[230:233], v[64:79]
	s_waitcnt vmcnt(5)
	v_mfma_f32_32x32x16_bf16 v[80:95], v[116:119], v[234:237], v[80:95]
	s_waitcnt vmcnt(4)
	v_mfma_f32_32x32x16_bf16 v[64:79], v[116:119], v[238:241], v[64:79]
	s_waitcnt vmcnt(3)
	v_mfma_f32_32x32x16_bf16 v[80:95], v[120:123], v[242:245], v[80:95]
	s_waitcnt vmcnt(2)
	v_mfma_f32_32x32x16_bf16 v[64:79], v[120:123], v[246:249], v[64:79]
	s_waitcnt vmcnt(1)
	v_mfma_f32_32x32x16_bf16 v[80:95], v[124:127], v[144:147], v[80:95]
	ds_read_b128 v[216:219], v213
	s_waitcnt vmcnt(0)
	v_mfma_f32_32x32x16_bf16 v[64:79], v[124:127], v[226:229], v[64:79]
	ds_read_b128 v[144:147], v128
	s_waitcnt lgkmcnt(0)
	v_mul_f32_e32 v128, 0x3fb8aa3b, v144
	v_exp_f32_e32 v144, v128
	v_mul_f32_e32 v128, 0x3fb8aa3b, v145
	v_exp_f32_e32 v145, v128
	v_mul_f32_e32 v128, 0x3fb8aa3b, v146
	v_exp_f32_e32 v146, v128
	v_mul_f32_e32 v128, 0x3fb8aa3b, v147
	v_exp_f32_e32 v147, v128
	v_mul_f32_e32 v128, 0x3fb8aa3b, v216
	v_exp_f32_e32 v220, v128
	v_mul_f32_e32 v128, 0x3fb8aa3b, v217
	v_exp_f32_e32 v221, v128
	v_mul_f32_e32 v128, 0x3fb8aa3b, v218
	v_exp_f32_e32 v222, v128
	v_mul_f32_e32 v128, 0x3fb8aa3b, v219
	ds_read_b128 v[216:219], v214
	v_exp_f32_e32 v223, v128
	v_pk_mul_f32 v[80:81], v[80:81], v[144:145]
	v_pk_mul_f32 v[84:85], v[84:85], v[220:221]
	v_pk_mul_f32 v[82:83], v[82:83], v[146:147]
	s_waitcnt lgkmcnt(0)
	v_mul_f32_e32 v128, 0x3fb8aa3b, v216
	v_exp_f32_e32 v224, v128
	v_mul_f32_e32 v128, 0x3fb8aa3b, v217
	ds_read_b128 v[214:217], v215
	v_exp_f32_e32 v225, v128
	v_mul_f32_e32 v128, 0x3fb8aa3b, v218
	v_exp_f32_e32 v218, v128
	v_mul_f32_e32 v128, 0x3fb8aa3b, v219
	v_exp_f32_e32 v219, v128
	s_waitcnt lgkmcnt(0)
	v_mul_f32_e32 v128, 0x3fb8aa3b, v214
	v_exp_f32_e32 v214, v128
	v_mul_f32_e32 v128, 0x3fb8aa3b, v215
	v_exp_f32_e32 v215, v128
	v_mul_f32_e32 v128, 0x3fb8aa3b, v216
	v_exp_f32_e32 v216, v128
	v_mul_f32_e32 v128, 0x3fb8aa3b, v217
	v_exp_f32_e32 v217, v128
	v_pk_mul_f32 v[92:93], v[92:93], v[214:215]
	v_pk_mul_f32 v[90:91], v[90:91], v[218:219]
	v_pk_mul_f32 v[88:89], v[88:89], v[224:225]
	v_pk_mul_f32 v[94:95], v[94:95], v[216:217]
	v_pk_mul_f32 v[86:87], v[86:87], v[222:223]
	v_pk_mul_f32 v[78:79], v[78:79], v[216:217]
	v_pk_mul_f32 v[76:77], v[76:77], v[214:215]
	v_pk_mul_f32 v[74:75], v[74:75], v[218:219]
	v_pk_mul_f32 v[72:73], v[72:73], v[224:225]
	v_pk_mul_f32 v[70:71], v[70:71], v[222:223]
	v_pk_mul_f32 v[68:69], v[68:69], v[220:221]
	v_pk_mul_f32 v[66:67], v[66:67], v[146:147]
	v_pk_mul_f32 v[64:65], v[64:65], v[144:145]
	s_and_saveexec_b64 vcc, s[0:1]
	s_cbranch_execnz .LBB0_601
	s_or_b64 exec, exec, vcc
	s_and_saveexec_b64 vcc, s[0:1]
	s_cbranch_execnz .LBB0_602
